# phase1: Mcat table trips pulled from an LDS work counter by all 8 waves (row waves join after their rows)
# speedup vs baseline: 1.0107x; 1.0107x over previous
.LBB0_71:
	s_or_b64 exec, exec, s[0:1]
	v_mov_b32_e32 v4, v193
	v_mov_b32_e32 v10, 0x20fe0
	v_mov_b32_e32 v11, 0
	ds_write_b32 v10, v11
	s_waitcnt lgkmcnt(0)
	s_barrier
	v_readlane_b32 s94, v248, 1
	v_readfirstlane_b32 s0, v4
	s_ashr_i32 s38, s0, 6
	v_and_b32_e32 v64, 63, v4
	s_cmp_gt_i32 s38, 3
	s_mov_b64 s[0:1], -1
	v_readlane_b32 s95, v248, 2
	s_cbranch_scc0 .LBB0_168
	s_lshl_b32 s0, s6, 2
	s_add_i32 s2, s38, -4
	s_add_i32 s94, s2, s0
	s_lshl_b32 s95, s92, 2
	s_cmpk_gt_i32 s94, 0x7ff
	s_cbranch_scc1 .LBB0_75
	s_mul_i32 s0, s2, 0x2400
	v_lshrrev_b32_e32 v5, 5, v64
	v_lshlrev_b32_e32 v1, 2, v4
	s_add_i32 s3, s0, 0
	v_mul_u32_u24_e32 v0, 0x84, v5
	v_and_b32_e32 v2, 0x7c, v1
	v_add3_u32 v6, s3, v0, v2
	v_lshlrev_b32_e32 v0, 3, v64
	v_lshrrev_b32_e32 v70, 3, v64
	v_and_b32_e32 v0, 56, v0
	v_mul_u32_u24_e32 v3, 0x84, v0
	v_lshlrev_b32_e32 v72, 1, v0
	v_mov_b32_e32 v73, 0
	v_lshlrev_b32_e32 v71, 2, v70
	v_lshl_add_u64 v[0:1], s[90:91], 0, v[72:73]
	s_mov_b64 s[0:1], 0x60000
	v_add3_u32 v71, s3, v3, v71
	v_mov_b32_e32 v3, v73
	v_or_b32_e32 v7, 2, v5
	v_add_u32_e32 v8, 0x108, v6
	v_or_b32_e32 v9, 4, v5
	v_add_u32_e32 v10, 0x210, v6
	v_or_b32_e32 v11, 6, v5
	v_add_u32_e32 v12, 0x318, v6
	v_or_b32_e32 v13, 8, v5
	v_add_u32_e32 v14, 0x420, v6
	v_or_b32_e32 v15, 10, v5
	v_add_u32_e32 v16, 0x528, v6
	v_or_b32_e32 v17, 12, v5
	v_add_u32_e32 v18, 0x630, v6
	v_or_b32_e32 v19, 14, v5
	v_add_u32_e32 v20, 0x738, v6
	v_or_b32_e32 v21, 16, v5
	v_add_u32_e32 v22, 0x840, v6
	v_or_b32_e32 v23, 18, v5
	v_add_u32_e32 v24, 0x948, v6
	v_or_b32_e32 v25, 20, v5
	v_add_u32_e32 v26, 0xa50, v6
	v_or_b32_e32 v27, 22, v5
	v_add_u32_e32 v28, 0xb58, v6
	v_or_b32_e32 v29, 24, v5
	v_add_u32_e32 v30, 0xc60, v6
	v_or_b32_e32 v31, 26, v5
	v_add_u32_e32 v32, 0xd68, v6
	v_or_b32_e32 v33, 28, v5
	v_add_u32_e32 v34, 0xe70, v6
	v_or_b32_e32 v35, 30, v5
	v_add_u32_e32 v36, 0xf78, v6
	v_or_b32_e32 v37, 32, v5
	v_add_u32_e32 v38, 0x1080, v6
	v_or_b32_e32 v39, 34, v5
	v_add_u32_e32 v40, 0x1188, v6
	v_or_b32_e32 v41, 36, v5
	v_add_u32_e32 v42, 0x1290, v6
	v_or_b32_e32 v43, 38, v5
	v_add_u32_e32 v44, 0x1398, v6
	v_or_b32_e32 v45, 40, v5
	v_add_u32_e32 v46, 0x14a0, v6
	v_or_b32_e32 v47, 42, v5
	v_add_u32_e32 v48, 0x15a8, v6
	v_or_b32_e32 v49, 44, v5
	v_add_u32_e32 v50, 0x16b0, v6
	v_or_b32_e32 v51, 46, v5
	v_add_u32_e32 v52, 0x17b8, v6
	v_or_b32_e32 v53, 48, v5
	v_add_u32_e32 v54, 0x18c0, v6
	v_or_b32_e32 v55, 50, v5
	v_add_u32_e32 v56, 0x19c8, v6
	v_or_b32_e32 v57, 52, v5
	v_add_u32_e32 v58, 0x1ad0, v6
	v_or_b32_e32 v59, 54, v5
	v_add_u32_e32 v60, 0x1bd8, v6
	v_or_b32_e32 v61, 56, v5
	v_add_u32_e32 v62, 0x1ce0, v6
	v_or_b32_e32 v63, 58, v5
	v_add_u32_e32 v65, 0x1de8, v6
	v_or_b32_e32 v66, 60, v5
	v_add_u32_e32 v67, 0x1ef0, v6
	v_or_b32_e32 v68, 62, v5
	v_add_u32_e32 v69, 0x1ff8, v6
	v_lshl_add_u64 v[0:1], v[0:1], 0, s[0:1]
	v_lshl_add_u64 v[2:3], s[48:49], 0, v[2:3]
	s_lshl_b32 s3, s94, 5
	s_lshl_b32 s7, s95, 5
	s_mov_b32 s8, s94

.Lmcat_setup:
	s_add_u32 s4, s90, 0x1d60000
	s_addc_u32 s5, s91, 0
	s_add_u32 s8, s90, 0x1f60000
	s_addc_u32 s9, s91, 0
	s_add_u32 s10, s90, 0x3fe0000
	s_addc_u32 s11, s91, 0
	s_mov_b64 s[12:13], 0
	s_mov_b32 s2, 0x2aaaaaab
	s_movk_i32 s3, 0xc0
	s_movk_i32 s7, 0x7f
	s_movk_i32 s18, 0x80
	v_mov_b32_e32 v0, 0
	s_movk_i32 s19, 0x600
	s_mov_b32 s33, 0x2fffff
	s_branch .Lmcat_fetch

.LBB0_124:
	s_or_b64 exec, exec, s[14:15]
	v_cvt_pk_bf16_f32 v2, v2, v3
	v_cvt_pk_bf16_f32 v3, v4, v5
	v_mov_b64_e32 v[4:5], s[8:9]
	v_cvt_pk_bf16_f32 v12, v12, v13
	v_cvt_pk_bf16_f32 v13, v10, v11
	v_mad_i64_i32 v[10:11], s[14:15], v7, s19, v[4:5]
	v_ashrrev_i32_e32 v9, 31, v8
	v_lshl_add_u64 v[8:9], v[8:9], 1, v[10:11]
	global_store_dwordx2 v[8:9], v[12:13], off
	v_mad_i64_i32 v[8:9], s[14:15], v15, s19, v[4:5]
	v_ashrrev_i32_e32 v15, 31, v14
	v_cvt_pk_bf16_f32 v18, v18, v19
	v_cvt_pk_bf16_f32 v19, v16, v17
	v_lshl_add_u64 v[8:9], v[14:15], 1, v[8:9]
	global_store_dwordx2 v[8:9], v[18:19], off
	v_mad_i64_i32 v[8:9], s[14:15], v21, s19, v[4:5]
	v_ashrrev_i32_e32 v21, 31, v20
	v_cvt_pk_bf16_f32 v24, v24, v25
	v_cvt_pk_bf16_f32 v25, v22, v23
	v_lshl_add_u64 v[8:9], v[20:21], 1, v[8:9]
	global_store_dwordx2 v[8:9], v[24:25], off
	v_mad_i64_i32 v[4:5], s[14:15], v27, s19, v[4:5]
	v_ashrrev_i32_e32 v27, 31, v26
	v_lshl_add_u64 v[4:5], v[26:27], 1, v[4:5]
	global_store_dwordx2 v[4:5], v[2:3], off
.Lmcat_fetch:
	s_mov_b64 exec, 1
	v_mov_b32_e32 v10, 0x20fe0
	v_mov_b32_e32 v11, 1
	ds_add_rtn_u32 v10, v10, v11
	s_waitcnt lgkmcnt(0)
	v_readfirstlane_b32 s98, v10
	s_mov_b64 exec, -1
	s_nop 0
	s_cmp_ge_u32 s98, 48
	s_cbranch_scc1 .Lmcat_done
	s_and_b32 s99, s98, 3
	s_lshr_b32 s98, s98, 2
	s_lshl_b32 s100, s6, 2
	s_add_i32 s99, s99, s100
	s_lshl_b32 s99, s99, 6
	s_lshl_b32 s98, s98, 18
	s_add_i32 s99, s99, s98
	v_or_b32_e32 v9, s99, v64
	s_branch .LBB0_125
.Lmcat_done:
	s_cmp_gt_i32 s38, 3
	s_cbranch_scc1 .LBB0_164
	s_branch .LBB0_172

.LBB0_171:
	global_load_dwordx4 v[46:49], v[32:33], off offset:-4096 nt
	global_load_dwordx4 v[24:27], v[32:33], off offset:-3072 nt
	global_load_dwordx4 v[16:19], v[32:33], off offset:-1024 nt
	global_load_dwordx4 v[20:23], v[32:33], off offset:-2048 nt
	global_load_dwordx4 v[12:15], v[32:33], off nt
	global_load_dwordx4 v[8:11], v[32:33], off offset:1024 nt
	global_load_dwordx4 v[4:7], v[32:33], off offset:2048 nt
	global_load_dwordx4 v[0:3], v[32:33], off offset:3072 nt
	s_ashr_i32 s0, s4, 11
	s_mul_i32 s0, s0, 6
	s_ashr_i32 s1, s0, 31
	s_lshl_b64 s[0:1], s[0:1], 12
	s_add_u32 s14, s90, s0
	s_addc_u32 s15, s91, s1
	s_add_u32 s16, s14, 0x1000
	s_addc_u32 s17, s15, 0
	global_load_dwordx4 v[50:53], v[28:29], off
	global_load_dwordx4 v[54:57], v42, s[14:15]
	global_load_dwordx4 v[58:61], v42, s[16:17]
	s_add_i32 s4, s4, s8
	v_lshl_add_u64 v[32:33], v[32:33], 0, s[12:13]
	s_cmpk_gt_i32 s4, 0x7fff
	s_waitcnt vmcnt(10)
	v_pk_mul_f32 v[62:63], v[48:49], v[48:49]
	v_pk_mul_f32 v[64:65], v[46:47], v[46:47]
	s_waitcnt vmcnt(9)
	v_pk_mul_f32 v[66:67], v[26:27], v[26:27]
	v_pk_mul_f32 v[68:69], v[24:25], v[24:25]
	v_pk_mov_b32 v[74:75], v[64:65], v[62:63] op_sel:[1,0]
	v_mov_b32_e32 v65, v63
	v_pk_mov_b32 v[62:63], v[68:69], v[66:67] op_sel:[1,0]
	v_mov_b32_e32 v69, v67
	s_waitcnt vmcnt(8)
	v_mul_f32_e32 v73, v16, v16
	s_waitcnt vmcnt(7)
	v_mul_f32_e32 v70, v21, v21
	v_mul_f32_e32 v72, v23, v23
	v_pk_add_f32 v[64:65], v[74:75], v[64:65]
	v_pk_add_f32 v[62:63], v[62:63], v[68:69]
	v_mul_f32_e32 v76, v17, v17
	v_mul_f32_e32 v77, v18, v18
	v_mul_f32_e32 v78, v19, v19
	v_pk_fma_f32 v[66:67], v[20:21], v[20:21], v[70:71] op_sel_hi:[1,1,0]
	v_pk_fma_f32 v[70:71], v[22:23], v[22:23], v[72:73] op_sel_hi:[1,1,0]
	v_pk_add_f32 v[64:65], v[64:65], v[64:65] op_sel:[0,1] op_sel_hi:[1,0]
	v_pk_add_f32 v[62:63], v[62:63], v[62:63] op_sel:[0,1] op_sel_hi:[1,0]
	v_mov_b32_e32 v67, v77
	v_mov_b32_e32 v71, v78
	v_mov_b32_e32 v65, v73
	v_mov_b32_e32 v63, v76
	v_pk_add_f32 v[66:67], v[66:67], v[70:71]
	v_pk_add_f32 v[62:63], v[64:65], v[62:63]
	s_waitcnt vmcnt(0)
	v_pk_add_f32 v[58:59], v[58:59], 1.0 op_sel_hi:[1,0]
	v_pk_add_f32 v[62:63], v[62:63], v[66:67]
	v_pk_add_f32 v[60:61], v[60:61], 1.0 op_sel_hi:[1,0]
	v_add_f32_e32 v62, v62, v63
	ds_bpermute_b32 v63, v34, v62
	s_waitcnt lgkmcnt(0)
	v_add_f32_e32 v62, v62, v63
	ds_bpermute_b32 v63, v35, v62
	s_waitcnt lgkmcnt(0)
	v_add_f32_e32 v62, v62, v63
	ds_bpermute_b32 v63, v36, v62
	s_waitcnt lgkmcnt(0)
	v_add_f32_e32 v62, v62, v63
	ds_bpermute_b32 v63, v37, v62
	s_waitcnt lgkmcnt(0)
	v_add_f32_e32 v62, v62, v63
	ds_bpermute_b32 v63, v38, v62
	s_waitcnt lgkmcnt(0)
	v_add_f32_e32 v62, v62, v63
	ds_bpermute_b32 v63, v39, v62
	s_waitcnt lgkmcnt(0)
	v_add_f32_e32 v62, v62, v63
	v_fmamk_f32 v62, v62, 0x3a800000, v40
	v_mul_f32_e32 v63, 0x4f800000, v62
	v_cmp_gt_f32_e32 vcc, s2, v62
	s_nop 1
	v_cndmask_b32_e32 v62, v62, v63, vcc
	v_sqrt_f32_e32 v63, v62
	s_nop 0
	v_add_u32_e32 v64, -1, v63
	v_add_u32_e32 v65, 1, v63
	v_fma_f32 v66, -v64, v63, v62
	v_fma_f32 v67, -v65, v63, v62
	v_cmp_ge_f32_e64 s[0:1], 0, v66
	s_nop 1
	v_cndmask_b32_e64 v63, v63, v64, s[0:1]
	v_cmp_lt_f32_e64 s[0:1], 0, v67
	s_nop 1
	v_cndmask_b32_e64 v63, v63, v65, s[0:1]
	v_mul_f32_e32 v64, 0x37800000, v63
	v_cndmask_b32_e32 v63, v63, v64, vcc
	v_cmp_class_f32_e32 vcc, v62, v41
	s_nop 1
	v_cndmask_b32_e32 v62, v63, v62, vcc
	v_div_scale_f32 v63, s[0:1], v62, v62, 1.0
	v_rcp_f32_e32 v65, v63
	v_div_scale_f32 v64, vcc, 1.0, v62, 1.0
	v_fma_f32 v66, -v63, v65, 1.0
	v_fmac_f32_e32 v65, v66, v65
	v_mul_f32_e32 v66, v64, v65
	v_fma_f32 v67, -v63, v66, v64
	v_fmac_f32_e32 v66, v67, v65
	v_fma_f32 v63, -v63, v66, v64
	v_div_fmas_f32 v63, v63, v65, v66
	v_div_fixup_f32 v62, v63, v62, 1.0
	v_pk_mul_f32 v[46:47], v[46:47], v[62:63] op_sel_hi:[1,0]
	v_pk_mul_f32 v[48:49], v[48:49], v[62:63] op_sel_hi:[1,0]
	v_pk_mul_f32 v[46:47], v[50:51], v[46:47]
	v_pk_mul_f32 v[48:49], v[52:53], v[48:49]
	v_pk_fma_f32 v[46:47], v[58:59], v[46:47], v[54:55]
	v_pk_fma_f32 v[48:49], v[60:61], v[48:49], v[56:57]
	v_cvt_pk_bf16_f32 v46, v46, v47
	v_cvt_pk_bf16_f32 v47, v48, v49
	global_store_dwordx2 v[30:31], v[46:47], off offset:-3584
	global_load_dwordx4 v[46:49], v[28:29], off offset:1024
	s_nop 0
	global_load_dwordx4 v[50:53], v43, s[16:17]
	global_load_dwordx4 v[54:57], v42, s[14:15] offset:1024
	v_pk_mul_f32 v[24:25], v[24:25], v[62:63] op_sel_hi:[1,0]
	v_pk_mul_f32 v[26:27], v[26:27], v[62:63] op_sel_hi:[1,0]
	v_pk_mul_f32 v[20:21], v[20:21], v[62:63] op_sel_hi:[1,0]
	v_pk_mul_f32 v[22:23], v[22:23], v[62:63] op_sel_hi:[1,0]
	v_mul_f32_e32 v63, v1, v1
	v_pk_mul_f32 v[16:17], v[16:17], v[62:63] op_sel_hi:[1,0]
	v_pk_mul_f32 v[18:19], v[18:19], v[62:63] op_sel_hi:[1,0]
	v_mul_f32_e32 v61, v0, v0
	v_mul_f32_e32 v58, v5, v5
	v_mul_f32_e32 v60, v7, v7
	v_mul_f32_e32 v66, v2, v2
	v_mul_f32_e32 v67, v3, v3
	s_waitcnt vmcnt(2)
	v_pk_mul_f32 v[24:25], v[46:47], v[24:25]
	s_waitcnt vmcnt(1)
	v_pk_add_f32 v[46:47], v[50:51], 1.0 op_sel_hi:[1,0]
	v_pk_mul_f32 v[26:27], v[48:49], v[26:27]
	v_pk_add_f32 v[48:49], v[52:53], 1.0 op_sel_hi:[1,0]
	s_waitcnt vmcnt(0)
	v_pk_fma_f32 v[24:25], v[24:25], v[46:47], v[54:55]
	v_pk_fma_f32 v[26:27], v[26:27], v[48:49], v[56:57]
	v_cvt_pk_bf16_f32 v24, v24, v25
	v_cvt_pk_bf16_f32 v25, v26, v27
	global_store_dwordx2 v[30:31], v[24:25], off offset:-3072
	global_load_dwordx4 v[24:27], v[28:29], off offset:2048
	s_nop 0
	global_load_dwordx4 v[46:49], v44, s[16:17]
	global_load_dwordx4 v[50:53], v42, s[14:15] offset:2048
	v_pk_mul_f32 v[54:55], v[10:11], v[10:11]
	v_pk_mul_f32 v[56:57], v[8:9], v[8:9]
	s_waitcnt vmcnt(2)
	v_pk_mul_f32 v[20:21], v[20:21], v[24:25]
	s_waitcnt vmcnt(1)
	v_pk_add_f32 v[24:25], v[46:47], 1.0 op_sel_hi:[1,0]
	v_pk_mul_f32 v[22:23], v[22:23], v[26:27]
	v_pk_add_f32 v[26:27], v[48:49], 1.0 op_sel_hi:[1,0]
	s_waitcnt vmcnt(0)
	v_pk_fma_f32 v[20:21], v[20:21], v[24:25], v[50:51]
	v_pk_fma_f32 v[22:23], v[22:23], v[26:27], v[52:53]
	v_cvt_pk_bf16_f32 v20, v20, v21
	v_cvt_pk_bf16_f32 v21, v22, v23
	global_store_dwordx2 v[30:31], v[20:21], off offset:-2560
	global_load_dwordx4 v[20:23], v[28:29], off offset:3072
	s_nop 0
	global_load_dwordx4 v[24:27], v45, s[16:17]
	global_load_dwordx4 v[46:49], v42, s[14:15] offset:3072
	v_pk_mul_f32 v[50:51], v[14:15], v[14:15]
	v_pk_mul_f32 v[52:53], v[12:13], v[12:13]
	s_waitcnt vmcnt(2)
	v_pk_mul_f32 v[16:17], v[16:17], v[20:21]
	s_waitcnt vmcnt(1)
	v_pk_add_f32 v[20:21], v[24:25], 1.0 op_sel_hi:[1,0]
	v_pk_mul_f32 v[18:19], v[18:19], v[22:23]
	v_pk_add_f32 v[22:23], v[26:27], 1.0 op_sel_hi:[1,0]
	s_waitcnt vmcnt(0)
	v_pk_fma_f32 v[16:17], v[16:17], v[20:21], v[46:47]
	v_pk_fma_f32 v[18:19], v[18:19], v[22:23], v[48:49]
	v_cvt_pk_bf16_f32 v16, v16, v17
	v_cvt_pk_bf16_f32 v17, v18, v19
	global_store_dwordx2 v[30:31], v[16:17], off offset:-2048
	global_load_dwordx4 v[16:19], v[28:29], off
	s_nop 0
	global_load_dwordx4 v[20:23], v42, s[16:17]
	global_load_dwordx4 v[24:27], v42, s[14:15]
	v_pk_mov_b32 v[64:65], v[52:53], v[50:51] op_sel:[1,0]
	v_mov_b32_e32 v53, v51
	v_pk_mov_b32 v[50:51], v[56:57], v[54:55] op_sel:[1,0]
	v_mov_b32_e32 v57, v55
	v_pk_add_f32 v[52:53], v[64:65], v[52:53]
	v_pk_add_f32 v[50:51], v[50:51], v[56:57]
	v_pk_fma_f32 v[54:55], v[4:5], v[4:5], v[58:59] op_sel_hi:[1,1,0]
	v_pk_fma_f32 v[58:59], v[6:7], v[6:7], v[60:61] op_sel_hi:[1,1,0]
	v_pk_add_f32 v[52:53], v[52:53], v[52:53] op_sel:[0,1] op_sel_hi:[1,0]
	v_pk_add_f32 v[50:51], v[50:51], v[50:51] op_sel:[0,1] op_sel_hi:[1,0]
	v_mov_b32_e32 v55, v66
	v_mov_b32_e32 v59, v67
	v_mov_b32_e32 v53, v61
	v_mov_b32_e32 v51, v63
	v_pk_add_f32 v[54:55], v[54:55], v[58:59]
	v_pk_add_f32 v[50:51], v[52:53], v[50:51]
	s_nop 0
	v_pk_add_f32 v[50:51], v[50:51], v[54:55]
	s_nop 0
	v_add_f32_e32 v50, v50, v51
	ds_bpermute_b32 v51, v34, v50
	s_waitcnt lgkmcnt(0)
	v_add_f32_e32 v50, v50, v51
	ds_bpermute_b32 v51, v35, v50
	s_waitcnt lgkmcnt(0)
	v_add_f32_e32 v50, v50, v51
	ds_bpermute_b32 v51, v36, v50
	s_waitcnt lgkmcnt(0)
	v_add_f32_e32 v46, v50, v51
	ds_bpermute_b32 v47, v37, v46
	s_waitcnt lgkmcnt(0)
	v_add_f32_e32 v46, v46, v47
	ds_bpermute_b32 v47, v38, v46
	s_waitcnt lgkmcnt(0)
	v_add_f32_e32 v46, v46, v47
	ds_bpermute_b32 v47, v39, v46
	s_waitcnt lgkmcnt(0)
	v_add_f32_e32 v46, v46, v47
	v_fmamk_f32 v46, v46, 0x3a800000, v40
	v_mul_f32_e32 v47, 0x4f800000, v46
	v_cmp_gt_f32_e32 vcc, s2, v46
	s_nop 1
	v_cndmask_b32_e32 v46, v46, v47, vcc
	v_sqrt_f32_e32 v47, v46
	s_nop 0
	v_add_u32_e32 v48, -1, v47
	v_add_u32_e32 v49, 1, v47
	v_fma_f32 v50, -v48, v47, v46
	v_fma_f32 v51, -v49, v47, v46
	v_cmp_ge_f32_e64 s[0:1], 0, v50
	s_nop 1
	v_cndmask_b32_e64 v47, v47, v48, s[0:1]
	v_cmp_lt_f32_e64 s[0:1], 0, v51
	s_nop 1
	v_cndmask_b32_e64 v47, v47, v49, s[0:1]
	v_mul_f32_e32 v48, 0x37800000, v47
	v_cndmask_b32_e32 v47, v47, v48, vcc
	v_cmp_class_f32_e32 vcc, v46, v41
	s_nop 1
	v_cndmask_b32_e32 v46, v47, v46, vcc
	v_div_scale_f32 v47, s[0:1], v46, v46, 1.0
	v_rcp_f32_e32 v49, v47
	v_div_scale_f32 v48, vcc, 1.0, v46, 1.0
	v_fma_f32 v50, -v47, v49, 1.0
	v_fmac_f32_e32 v49, v50, v49
	v_mul_f32_e32 v50, v48, v49
	v_fma_f32 v51, -v47, v50, v48
	v_fmac_f32_e32 v50, v51, v49
	v_fma_f32 v47, -v47, v50, v48
	v_div_fmas_f32 v47, v47, v49, v50
	v_div_fixup_f32 v46, v47, v46, 1.0
	v_pk_mul_f32 v[12:13], v[12:13], v[46:47] op_sel_hi:[1,0]
	v_pk_mul_f32 v[14:15], v[14:15], v[46:47] op_sel_hi:[1,0]
	s_waitcnt vmcnt(2)
	v_pk_mul_f32 v[12:13], v[16:17], v[12:13]
	s_waitcnt vmcnt(1)
	v_pk_add_f32 v[16:17], v[20:21], 1.0 op_sel_hi:[1,0]
	v_pk_mul_f32 v[14:15], v[18:19], v[14:15]
	v_pk_add_f32 v[18:19], v[22:23], 1.0 op_sel_hi:[1,0]
	s_waitcnt vmcnt(0)
	v_pk_fma_f32 v[12:13], v[16:17], v[12:13], v[24:25]
	v_pk_fma_f32 v[14:15], v[18:19], v[14:15], v[26:27]
	v_cvt_pk_bf16_f32 v12, v12, v13
	v_cvt_pk_bf16_f32 v13, v14, v15
	global_store_dwordx2 v[30:31], v[12:13], off offset:-1536
	global_load_dwordx4 v[12:15], v[28:29], off offset:1024
	s_nop 0
	global_load_dwordx4 v[16:19], v43, s[16:17]
	global_load_dwordx4 v[20:23], v42, s[14:15] offset:1024
	v_pk_mul_f32 v[8:9], v[8:9], v[46:47] op_sel_hi:[1,0]
	v_pk_mul_f32 v[10:11], v[10:11], v[46:47] op_sel_hi:[1,0]
	v_pk_mul_f32 v[4:5], v[4:5], v[46:47] op_sel_hi:[1,0]
	v_pk_mul_f32 v[6:7], v[6:7], v[46:47] op_sel_hi:[1,0]
	v_pk_mul_f32 v[0:1], v[0:1], v[46:47] op_sel_hi:[1,0]
	v_pk_mul_f32 v[2:3], v[2:3], v[46:47] op_sel_hi:[1,0]
	s_waitcnt vmcnt(2)
	v_pk_mul_f32 v[8:9], v[12:13], v[8:9]
	s_waitcnt vmcnt(1)
	v_pk_add_f32 v[12:13], v[16:17], 1.0 op_sel_hi:[1,0]
	v_pk_mul_f32 v[10:11], v[14:15], v[10:11]
	v_pk_add_f32 v[14:15], v[18:19], 1.0 op_sel_hi:[1,0]
	s_waitcnt vmcnt(0)
	v_pk_fma_f32 v[8:9], v[8:9], v[12:13], v[20:21]
	v_pk_fma_f32 v[10:11], v[10:11], v[14:15], v[22:23]
	v_cvt_pk_bf16_f32 v8, v8, v9
	v_cvt_pk_bf16_f32 v9, v10, v11
	global_store_dwordx2 v[30:31], v[8:9], off offset:-1024
	global_load_dwordx4 v[8:11], v[28:29], off offset:2048
	s_nop 0
	global_load_dwordx4 v[12:15], v44, s[16:17]
	global_load_dwordx4 v[16:19], v42, s[14:15] offset:2048
	s_waitcnt vmcnt(2)
	v_pk_mul_f32 v[4:5], v[4:5], v[8:9]
	s_waitcnt vmcnt(1)
	v_pk_add_f32 v[8:9], v[12:13], 1.0 op_sel_hi:[1,0]
	v_pk_mul_f32 v[6:7], v[6:7], v[10:11]
	v_pk_add_f32 v[10:11], v[14:15], 1.0 op_sel_hi:[1,0]
	s_waitcnt vmcnt(0)
	v_pk_fma_f32 v[4:5], v[4:5], v[8:9], v[16:17]
	v_pk_fma_f32 v[6:7], v[6:7], v[10:11], v[18:19]
	v_cvt_pk_bf16_f32 v4, v4, v5
	v_cvt_pk_bf16_f32 v5, v6, v7
	global_store_dwordx2 v[30:31], v[4:5], off offset:-512
	global_load_dwordx4 v[4:7], v[28:29], off offset:3072
	s_nop 0
	global_load_dwordx4 v[8:11], v45, s[16:17]
	global_load_dwordx4 v[12:15], v42, s[14:15] offset:3072
	s_waitcnt vmcnt(2)
	v_pk_mul_f32 v[0:1], v[0:1], v[4:5]
	s_waitcnt vmcnt(1)
	v_pk_add_f32 v[4:5], v[8:9], 1.0 op_sel_hi:[1,0]
	v_pk_mul_f32 v[2:3], v[2:3], v[6:7]
	v_pk_add_f32 v[6:7], v[10:11], 1.0 op_sel_hi:[1,0]
	s_waitcnt vmcnt(0)
	v_pk_fma_f32 v[0:1], v[0:1], v[4:5], v[12:13]
	v_pk_fma_f32 v[2:3], v[2:3], v[6:7], v[14:15]
	v_cvt_pk_bf16_f32 v0, v0, v1
	v_cvt_pk_bf16_f32 v1, v2, v3
	global_store_dwordx2 v[30:31], v[0:1], off
	v_lshl_add_u64 v[30:31], v[30:31], 0, s[10:11]
	s_cbranch_scc0 .LBB0_171
	v_and_b32_e32 v64, 63, v193
	s_lshl_b32 s71, s92, 8
	s_branch .Lmcat_setup

	.amdhsa_kernel _Z4mega6Params
		.amdhsa_group_segment_fixed_size 0
		.amdhsa_private_segment_fixed_size 0
		.amdhsa_kernarg_size 544
		.amdhsa_user_sgpr_count 2
		.amdhsa_user_sgpr_dispatch_ptr 0
		.amdhsa_user_sgpr_queue_ptr 0
		.amdhsa_user_sgpr_kernarg_segment_ptr 1
		.amdhsa_user_sgpr_dispatch_id 0
		.amdhsa_user_sgpr_kernarg_preload_length 0
		.amdhsa_user_sgpr_kernarg_preload_offset 0
		.amdhsa_user_sgpr_private_segment_size 0
		.amdhsa_uses_dynamic_stack 0
		.amdhsa_enable_private_segment 0
		.amdhsa_system_sgpr_workgroup_id_x 1
		.amdhsa_system_sgpr_workgroup_id_y 0
		.amdhsa_system_sgpr_workgroup_id_z 0
		.amdhsa_system_sgpr_workgroup_info 0
		.amdhsa_system_vgpr_workitem_id 2
		.amdhsa_next_free_vgpr 249
		.amdhsa_next_free_sgpr 102
		.amdhsa_accum_offset 252
		.amdhsa_reserve_vcc 1
		.amdhsa_float_round_mode_32 0
		.amdhsa_float_round_mode_16_64 0
		.amdhsa_float_denorm_mode_32 3
		.amdhsa_float_denorm_mode_16_64 3
		.amdhsa_dx10_clamp 1
		.amdhsa_ieee_mode 1
		.amdhsa_fp16_overflow 0
		.amdhsa_tg_split 0
		.amdhsa_exception_fp_ieee_invalid_op 0
		.amdhsa_exception_fp_denorm_src 0
		.amdhsa_exception_fp_ieee_div_zero 0
		.amdhsa_exception_fp_ieee_overflow 0
		.amdhsa_exception_fp_ieee_underflow 0
		.amdhsa_exception_fp_ieee_inexact 0
		.amdhsa_exception_int_div_zero 0
	.end_amdhsa_kernel

amdhsa.kernels:
  - .agpr_count:     0
    .args:
      - .offset:         0
        .size:           288
        .value_kind:     by_value
      - .offset:         288
        .size:           4
        .value_kind:     hidden_block_count_x
      - .offset:         292
        .size:           4
        .value_kind:     hidden_block_count_y
      - .offset:         296
        .size:           4
        .value_kind:     hidden_block_count_z
      - .offset:         300
        .size:           2
        .value_kind:     hidden_group_size_x
      - .offset:         302
        .size:           2
        .value_kind:     hidden_group_size_y
      - .offset:         304
        .size:           2
        .value_kind:     hidden_group_size_z
      - .offset:         306
        .size:           2
        .value_kind:     hidden_remainder_x
      - .offset:         308
        .size:           2
        .value_kind:     hidden_remainder_y
      - .offset:         310
        .size:           2
        .value_kind:     hidden_remainder_z
      - .offset:         328
        .size:           8
        .value_kind:     hidden_global_offset_x
      - .offset:         336
        .size:           8
        .value_kind:     hidden_global_offset_y
      - .offset:         344
        .size:           8
        .value_kind:     hidden_global_offset_z
      - .offset:         352
        .size:           2
        .value_kind:     hidden_grid_dims
      - .offset:         376
        .size:           8
        .value_kind:     hidden_multigrid_sync_arg
      - .offset:         408
        .size:           4
        .value_kind:     hidden_dynamic_lds_size
    .group_segment_fixed_size: 0
    .kernarg_segment_align: 8
    .kernarg_segment_size: 544
    .language:       OpenCL C
    .language_version:
      - 2
      - 0
    .max_flat_workgroup_size: 512
    .name:           _Z4mega6Params
    .private_segment_fixed_size: 0
    .sgpr_count:     108
    .sgpr_spill_count: 24
    .symbol:         _Z4mega6Params.kd
    .uniform_work_group_size: 1
    .uses_dynamic_stack: false
    .vgpr_count:     249
    .vgpr_spill_count: 0
    .wavefront_size: 64
